# attention loop: packed f32 row-sum adds split into scalar adds, dead halves removed
# baseline (speedup 1.0000x reference)
.LBB0_1767:
	s_and_b32 s37, s39, 0x4000
	s_lshl_b32 s54, s54, 14
	s_add_i32 s37, s43, s37
	s_add_i32 s54, s54, 0
	v_add_u32_e32 v68, s37, v186
	v_add_u32_e32 v106, s54, v190
	v_add_u32_e32 v114, s54, v194
	ds_read_b128 v[64:67], v68
	ds_read_b128 v[80:83], v68 offset:4096
	v_add_u32_e32 v122, s54, v191
	v_add_u32_e32 v126, s54, v195
	ds_read_b64_tr_b16 v[102:103], v114 offset:32768
	ds_read_b64_tr_b16 v[100:101], v106 offset:32768
	ds_read_b64_tr_b16 v[104:105], v106 offset:36864
	ds_read_b64_tr_b16 v[108:109], v106 offset:40960
	ds_read_b64_tr_b16 v[112:113], v106 offset:45056
	ds_read_b64_tr_b16 v[106:107], v114 offset:36864
	ds_read_b64_tr_b16 v[110:111], v114 offset:40960
	ds_read_b64_tr_b16 v[114:115], v114 offset:45056
	ds_read_b64_tr_b16 v[118:119], v126 offset:32768
	ds_read_b64_tr_b16 v[116:117], v122 offset:32768
	ds_read_b64_tr_b16 v[120:121], v122 offset:36864
	v_add_u32_e32 v208, s54, v192
	v_add_u32_e32 v212, s54, v196
	s_waitcnt lgkmcnt(9)
	v_mfma_f32_32x32x16_bf16 v[0:15], v[100:103], v[156:159], v[0:15]
	ds_read_b64_tr_b16 v[100:101], v122 offset:40960
	ds_read_b64_tr_b16 v[124:125], v122 offset:45056
	ds_read_b64_tr_b16 v[122:123], v126 offset:36864
	ds_read_b64_tr_b16 v[102:103], v126 offset:40960
	ds_read_b64_tr_b16 v[126:127], v126 offset:45056
	ds_read_b64_tr_b16 v[202:203], v208 offset:32768
	ds_read_b64_tr_b16 v[204:205], v212 offset:32768
	v_add_u32_e32 v224, s54, v197
	v_add_u32_e32 v220, s54, v193
	v_add_u32_e32 v179, s37, v187
	s_mov_b32 s54, s53
	s_waitcnt lgkmcnt(8)
	v_mfma_f32_32x32x16_bf16 v[48:63], v[116:119], v[156:159], v[48:63]
	ds_read_b64_tr_b16 v[116:117], v208 offset:36864
	ds_read_b64_tr_b16 v[206:207], v208 offset:40960
	ds_read_b64_tr_b16 v[210:211], v208 offset:45056
	ds_read_b64_tr_b16 v[118:119], v212 offset:36864
	ds_read_b64_tr_b16 v[208:209], v212 offset:40960
	ds_read_b64_tr_b16 v[212:213], v212 offset:45056
	ds_read_b64_tr_b16 v[216:217], v224 offset:32768
	v_mfma_f32_32x32x16_bf16 v[64:79], v[64:67], v[144:147], 0
	v_mfma_f32_32x32x16_bf16 v[80:95], v[80:83], v[144:147], 0
	s_waitcnt lgkmcnt(7)
	v_mfma_f32_32x32x16_bf16 v[32:47], v[202:205], v[156:159], v[32:47]
	ds_read_b64_tr_b16 v[214:215], v220 offset:32768
	ds_read_b64_tr_b16 v[202:203], v220 offset:36864
	ds_read_b64_tr_b16 v[218:219], v220 offset:40960
	ds_read_b64_tr_b16 v[222:223], v220 offset:45056
	ds_read_b64_tr_b16 v[204:205], v224 offset:36864
	ds_read_b64_tr_b16 v[220:221], v224 offset:40960
	ds_read_b64_tr_b16 v[224:225], v224 offset:45056
	s_waitcnt lgkmcnt(6)
	v_mfma_f32_32x32x16_bf16 v[16:31], v[214:217], v[156:159], v[16:31]
	ds_read_b128 v[156:159], v179
	ds_read_b128 v[214:217], v179 offset:4096
	s_waitcnt lgkmcnt(1)
	v_mfma_f32_32x32x16_bf16 v[64:79], v[156:159], v[148:151], v[64:79]
	s_waitcnt lgkmcnt(0)
	v_mfma_f32_32x32x16_bf16 v[80:95], v[214:217], v[148:151], v[80:95]
	v_mfma_f32_32x32x16_bf16 v[32:47], v[116:119], v[136:139], v[32:47]
	v_add_u32_e32 v116, s37, v188
	v_mfma_f32_32x32x16_bf16 v[0:15], v[104:107], v[136:139], v[0:15]
	ds_read_b128 v[104:107], v116
	ds_read_b128 v[116:119], v116 offset:4096
	v_mfma_f32_32x32x16_bf16 v[48:63], v[120:123], v[136:139], v[48:63]
	s_waitcnt lgkmcnt(1)
	v_mfma_f32_32x32x16_bf16 v[64:79], v[104:107], v[152:155], v[64:79]
	v_add_u32_e32 v104, s37, v189
	s_add_i32 s37, s53, 1
	s_cmp_lg_u32 s53, 2
	s_cselect_b32 s53, s37, 0
	s_addk_i32 s39, 0x4000
	s_lshl_b32 s37, s53, 14
	s_add_i32 s38, s38, -1
	s_waitcnt lgkmcnt(0)
	v_mfma_f32_32x32x16_bf16 v[80:95], v[116:119], v[152:155], v[80:95]
	s_and_b32 s55, s39, 0x4000
	s_add_i32 s56, s37, 0
	v_add_u32_e32 v116, s55, v183
	s_cmp_eq_u32 s38, 0
	v_add_u32_e32 v117, s56, v182
	v_mfma_f32_32x32x16_bf16 v[48:63], v[100:103], v[132:135], v[48:63]
	ds_read_b128 v[100:103], v104
	ds_read_b128 v[104:107], v104 offset:4096
	v_mfma_f32_32x32x16_bf16 v[0:15], v[108:111], v[132:135], v[0:15]
	s_waitcnt lgkmcnt(1)
	v_mfma_f32_32x32x16_bf16 v[64:79], v[100:103], v[140:143], v[64:79]
	v_lshl_add_u64 v[100:101], v[98:99], 0, s[4:5]
	v_lshl_add_u64 v[102:103], v[96:97], 0, s[4:5]
	v_lshl_add_u64 v[96:97], v[96:97], 0, s[34:35]
	v_lshl_add_u64 v[98:99], v[98:99], 0, s[34:35]
	s_waitcnt lgkmcnt(0)
	v_mfma_f32_32x32x16_bf16 v[80:95], v[104:107], v[140:143], v[80:95]
	v_add_co_u32_e32 v104, vcc, s49, v100
	s_nop 4
	v_exp_f32_e32 v118, v64
	v_addc_co_u32_e32 v105, vcc, 0, v101, vcc
	v_add_co_u32_e32 v108, vcc, s49, v102
	v_mfma_f32_32x32x16_bf16 v[0:15], v[112:115], v[128:131], v[0:15]
	s_nop 0
	v_addc_co_u32_e32 v109, vcc, 0, v103, vcc
	v_add_co_u32_e32 v112, vcc, s50, v102
	v_exp_f32_e32 v65, v65
	s_nop 0
	v_addc_co_u32_e32 v113, vcc, 0, v103, vcc
	global_load_dwordx4 v[100:103], v[104:105], off
	s_nop 0
	global_load_dwordx4 v[104:107], v[104:105], off offset:128
	s_nop 0
	global_load_dwordx4 v[108:111], v[108:109], off offset:2048
	s_nop 0
	global_load_dwordx4 v[112:115], v[112:113], off offset:2048
	v_exp_f32_e32 v119, v66
	v_exp_f32_e32 v67, v67
	v_exp_f32_e32 v64, v68
	v_exp_f32_e32 v66, v69
	v_exp_f32_e32 v122, v81
	v_exp_f32_e32 v81, v82
	v_exp_f32_e32 v82, v92
	v_add_f32_e32 v92, v118, v65
	v_cvt_pk_bf16_f32 v156, v118, v65
	v_add_f32_e32 v65, v119, v67
	v_cvt_pk_bf16_f32 v157, v119, v67
	v_add_f32_e32 v67, v181, v92
	v_cvt_pk_bf16_f32 v158, v64, v66
	v_add_f32_e32 v64, v64, v66
	v_add_f32_e32 v65, v65, v67
	v_exp_f32_e32 v120, v70
	v_exp_f32_e32 v71, v71
	v_add_f32_e32 v65, v64, v65
	v_exp_f32_e32 v68, v72
	v_exp_f32_e32 v64, v73
	v_mfma_f32_32x32x16_bf16 v[16:31], v[202:205], v[136:139], v[16:31]
	v_exp_f32_e32 v74, v74
	v_exp_f32_e32 v121, v75
	v_exp_f32_e32 v70, v76
	v_exp_f32_e32 v72, v77
	v_add_f32_e32 v69, v120, v71
	v_add_f32_e32 v66, v68, v64
	v_add_f32_e32 v67, v69, v65
	v_exp_f32_e32 v77, v78
	v_exp_f32_e32 v79, v79
	v_cvt_pk_bf16_f32 v136, v68, v64
	v_add_f32_e32 v65, v66, v67
	v_exp_f32_e32 v75, v80
	v_cvt_pk_bf16_f32 v159, v120, v71
	v_add_f32_e32 v71, v74, v121
	v_mov_b32_e32 v73, v65
	v_add_f32_e32 v64, v70, v72
	v_add_f32_e32 v65, v71, v73
	v_exp_f32_e32 v83, v83
	v_add_f32_e32 v64, v64, v65
	v_mfma_f32_32x32x16_bf16 v[32:47], v[206:209], v[132:135], v[32:47]
	v_exp_f32_e32 v76, v84
	v_exp_f32_e32 v78, v85
	v_cvt_pk_bf16_f32 v137, v74, v121
	v_add_f32_e32 v74, v77, v79
	v_mov_b32_e32 v65, v122
	v_add_f32_e32 v64, v74, v64
	v_add_f32_e32 v65, v75, v65
	v_cvt_pk_bf16_f32 v139, v77, v79
	v_mfma_f32_32x32x16_bf16 v[16:31], v[218:221], v[132:135], v[16:31]
	v_add_f32_e32 v65, v64, v65
	v_add_f32_e32 v77, v81, v83
	v_mov_b32_e32 v79, v65
	v_add_f32_e32 v64, v76, v78
	v_add_f32_e32 v65, v77, v79
	v_exp_f32_e32 v85, v86
	v_exp_f32_e32 v86, v87
	v_add_f32_e32 v65, v64, v65
	v_exp_f32_e32 v80, v88
	v_exp_f32_e32 v64, v89
	v_mfma_f32_32x32x16_bf16 v[48:63], v[124:127], v[128:131], v[48:63]
	v_exp_f32_e32 v87, v90
	v_exp_f32_e32 v88, v91
	v_exp_f32_e32 v84, v93
	v_cvt_pk_bf16_f32 v133, v81, v83
	v_add_f32_e32 v81, v85, v86
	v_exp_f32_e32 v90, v94
	v_exp_f32_e32 v91, v95
	v_mfma_f32_32x32x16_bf16 v[32:47], v[210:213], v[128:131], v[32:47]
	v_add_f32_e64 v66, v80, v64
	v_add_f32_e64 v67, v81, v65
	v_cvt_pk_bf16_f32 v135, v85, v86
	v_add_f32_e32 v83, v87, v88
	v_add_f32_e32 v86, v90, v91
	v_cvt_pk_bf16_f32 v138, v70, v72
	v_cvt_pk_bf16_f32 v132, v75, v122
	v_cvt_pk_bf16_f32 v134, v76, v78
	v_mfma_f32_32x32x16_bf16 v[16:31], v[222:225], v[128:131], v[16:31]
	v_cvt_pk_bf16_f32 v128, v80, v64
	v_add_f32_e64 v64, v66, v66
	v_add_f32_e64 v65, v66, v67
	v_mov_b32_e32 v85, v65
	v_add_f32_e64 v64, v82, v84
	v_add_f32_e64 v65, v83, v85
	v_cvt_pk_bf16_f32 v129, v87, v88
	v_add_f32_e32 v64, v64, v65
	v_cvt_pk_bf16_f32 v130, v82, v84
	v_cvt_pk_bf16_f32 v131, v90, v91
	v_add_f32_e32 v181, v86, v64
	s_waitcnt vmcnt(3)
	ds_write_b128 v116, v[100:103]
	s_waitcnt vmcnt(2)
	ds_write_b128 v116, v[104:107] offset:8192
	s_waitcnt vmcnt(1)
	ds_write_b128 v117, v[108:111] offset:32768
	s_waitcnt vmcnt(0)
	ds_write_b128 v117, v[112:115] offset:40960
	s_waitcnt lgkmcnt(0)
	s_barrier
	s_cbranch_scc0 .LBB0_1767
	s_lshl_b32 s4, s54, 14
	s_branch .LBB0_1770
